# v36 + FFN1 SwiGLU epilogue rescheduled in original order with 2-3 chains interleaved (8 nops instead of 117), stores stay spread
# speedup vs baseline: 1.0049x; 1.0049x over previous
; __device__ __forceinline__ unsigned cvt_pk_bf16(float lo, float hi) { unsigned r; asm volatile("v_cvt_pk_bf16_f32 %0, %1, %2" : "=v"(r) : "v"(lo), "v"(hi)); return r; }
;     DI void operator()(const pg8::f32x4 (&acc)[2][2][4][2], const pg8::Unit& u, int wr, int wc, int fr, int fq) const {
;         const int row0 = u.pm * 256 + wr * 64 + fr, col0 = u.pn * 128 + wc * 32 + 8 * fq;
; #pragma unroll
;         for (int ai = 0; ai < 2; ++ai)
; #pragma unroll
;             for (int m = 0; m < 4; ++m) { bf16* rowp = O + (size_t)(row0 + ai * 128 + m * 16) * FF + col0;
;                 float hv[8];
; #pragma unroll
;                 for (int n = 0; n < 2; ++n)
; #pragma unroll
;                     for (int j = 0; j < 4; ++j) { const float g = acc[ai][0][m][n][j], up = acc[ai][1][m][n][j]; hv[4 * n + j] = g * __builtin_amdgcn_rcpf(1.f + __expf(-g)) * up; }
;                 v4u w; w.x = pg8::cvt_pk_bf16(hv[0], hv[1]); w.y = pg8::cvt_pk_bf16(hv[2], hv[3]); w.z = pg8::cvt_pk_bf16(hv[4], hv[5]); w.w = pg8::cvt_pk_bf16(hv[6], hv[7]);
;                 *(v4u*)rowp = w; }
.LBB0_1179:
	v_mul_f32_e32 v150, 0xbfb8aa3b, v124
	v_exp_f32_e32 v150, v150
	v_lshl_or_b32 v146, s33, 7, v142
	v_lshl_add_u32 v144, s34, 8, v140
	v_ashrrev_i32_e32 v147, 31, v146
	v_add_f32_e32 v150, 1.0, v150
	v_rcp_f32_e32 v150, v150
	v_mov_b64_e32 v[138:139], s[2:3]
	s_movk_i32 s7, 0x1600
	v_mad_i64_i32 v[148:149], s[14:15], v144, s7, v[138:139]
	v_mul_f32_e32 v124, v124, v150
	v_mul_f32_e32 v120, v124, v120
	v_mul_f32_e32 v151, 0xbfb8aa3b, v125
	v_exp_f32_e32 v151, v151
	s_andn2_b64 vcc, exec, s[42:43]
	v_add_f32_e32 v151, 1.0, v151
	v_rcp_f32_e32 v151, v151
	v_mul_f32_e32 v152, 0xbfb8aa3b, v126
	v_mul_f32_e32 v151, v125, v151
	v_mul_f32_e32 v121, v151, v121
	v_exp_f32_e32 v152, v152
	v_mul_f32_e32 v153, 0xbfb8aa3b, v127
	v_add_f32_e32 v152, 1.0, v152
	v_rcp_f32_e32 v152, v152
	v_exp_f32_e32 v153, v153
	v_mul_f32_e32 v152, v126, v152
	v_mul_f32_e32 v122, v152, v122
	v_add_f32_e32 v153, 1.0, v153
	v_rcp_f32_e32 v153, v153
	v_mul_f32_e32 v154, 0xbfb8aa3b, v116
	v_mul_f32_e32 v153, v127, v153
	v_mul_f32_e32 v123, v153, v123
	v_exp_f32_e32 v154, v154
	v_mul_f32_e32 v155, 0xbfb8aa3b, v117
	v_add_f32_e32 v154, 1.0, v154
	v_rcp_f32_e32 v154, v154
	v_exp_f32_e32 v155, v155
	v_mul_f32_e32 v116, v116, v154
	v_mul_f32_e32 v116, v116, v112
	v_add_f32_e32 v155, 1.0, v155
	v_rcp_f32_e32 v155, v155
	v_mul_f32_e32 v156, 0xbfb8aa3b, v118
	v_mul_f32_e32 v155, v117, v155
	v_mul_f32_e32 v117, v155, v113
	v_exp_f32_e32 v156, v156
	v_mul_f32_e32 v157, 0xbfb8aa3b, v119
	v_add_f32_e32 v156, 1.0, v156
	v_rcp_f32_e32 v156, v156
	v_exp_f32_e32 v157, v157
	v_mul_f32_e32 v156, v118, v156
	v_mul_f32_e32 v124, v156, v114
	v_cvt_pk_bf16_f32 v114, v120, v121
	v_add_f32_e32 v157, 1.0, v157
	v_rcp_f32_e32 v157, v157
	v_lshlrev_b64 v[112:113], 1, v[146:147]
	v_mul_f32_e32 v157, v119, v157
	v_mul_f32_e32 v125, v157, v115
	v_lshl_add_u64 v[118:119], v[148:149], 0, v[112:113]
	v_cvt_pk_bf16_f32 v115, v122, v123
	v_cvt_pk_bf16_f32 v116, v116, v117
	v_cvt_pk_bf16_f32 v117, v124, v125
	v_mul_f32_e32 v158, 0xbfb8aa3b, v108
	global_store_dwordx4 v[118:119], v[114:117], off
	v_exp_f32_e32 v158, v158
	s_nop 0
	v_or_b32_e32 v114, 16, v144
	v_mad_i64_i32 v[114:115], s[14:15], v114, s7, v[138:139]
	v_add_f32_e32 v158, 1.0, v158
	v_rcp_f32_e32 v158, v158
	v_mul_f32_e32 v159, 0xbfb8aa3b, v109
	v_mul_f32_e32 v108, v108, v158
	v_mul_f32_e32 v104, v108, v104
	v_exp_f32_e32 v159, v159
	v_mul_f32_e32 v160, 0xbfb8aa3b, v110
	v_add_f32_e32 v159, 1.0, v159
	v_rcp_f32_e32 v159, v159
	v_exp_f32_e32 v160, v160
	v_mul_f32_e32 v159, v109, v159
	v_mul_f32_e32 v105, v159, v105
	v_add_f32_e32 v160, 1.0, v160
	v_rcp_f32_e32 v160, v160
	v_mul_f32_e32 v161, 0xbfb8aa3b, v111
	v_mul_f32_e32 v160, v110, v160
	v_mul_f32_e32 v106, v160, v106
	v_exp_f32_e32 v161, v161
	v_mul_f32_e32 v162, 0xbfb8aa3b, v100
	v_add_f32_e32 v161, 1.0, v161
	v_rcp_f32_e32 v161, v161
	v_exp_f32_e32 v162, v162
	v_mul_f32_e32 v161, v111, v161
	v_mul_f32_e32 v107, v161, v107
	v_add_f32_e32 v162, 1.0, v162
	v_rcp_f32_e32 v162, v162
	v_mul_f32_e32 v163, 0xbfb8aa3b, v101
	v_mul_f32_e32 v100, v100, v162
	v_mul_f32_e32 v108, v100, v96
	v_exp_f32_e32 v163, v163
	v_mul_f32_e32 v164, 0xbfb8aa3b, v102
	v_add_f32_e32 v163, 1.0, v163
	v_rcp_f32_e32 v163, v163
	v_exp_f32_e32 v164, v164
	v_mul_f32_e32 v163, v101, v163
	v_mul_f32_e32 v109, v163, v97
	v_lshl_add_u64 v[100:101], v[114:115], 0, v[112:113]
	v_add_f32_e32 v164, 1.0, v164
	v_rcp_f32_e32 v164, v164
	v_mul_f32_e32 v165, 0xbfb8aa3b, v103
	v_mul_f32_e32 v164, v102, v164
	v_mul_f32_e32 v102, v164, v98
	v_exp_f32_e32 v165, v165
	v_cvt_pk_bf16_f32 v96, v104, v105
	v_add_f32_e32 v165, 1.0, v165
	v_rcp_f32_e32 v165, v165
	v_cvt_pk_bf16_f32 v97, v106, v107
	v_mul_f32_e32 v165, v103, v165
	v_mul_f32_e32 v99, v165, v99
	v_cvt_pk_bf16_f32 v98, v108, v109
	v_cvt_pk_bf16_f32 v99, v102, v99
	v_mul_f32_e32 v166, 0xbfb8aa3b, v92
	global_store_dwordx4 v[100:101], v[96:99], off
	v_exp_f32_e32 v166, v166
	s_nop 0
	v_or_b32_e32 v96, 32, v144
	v_mad_i64_i32 v[96:97], s[14:15], v96, s7, v[138:139]
	v_add_f32_e32 v166, 1.0, v166
	v_rcp_f32_e32 v166, v166
	v_mul_f32_e32 v167, 0xbfb8aa3b, v93
	v_mul_f32_e32 v92, v92, v166
	v_mul_f32_e32 v88, v92, v88
	v_exp_f32_e32 v167, v167
	v_mul_f32_e32 v168, 0xbfb8aa3b, v94
	v_add_f32_e32 v167, 1.0, v167
	v_rcp_f32_e32 v167, v167
	v_exp_f32_e32 v168, v168
	v_mul_f32_e32 v167, v93, v167
	v_mul_f32_e32 v89, v167, v89
	v_add_f32_e32 v168, 1.0, v168
	v_rcp_f32_e32 v168, v168
	v_mul_f32_e32 v169, 0xbfb8aa3b, v95
	v_mul_f32_e32 v168, v94, v168
	v_mul_f32_e32 v90, v168, v90
	v_exp_f32_e32 v169, v169
	v_mul_f32_e32 v170, 0xbfb8aa3b, v84
	v_add_f32_e32 v169, 1.0, v169
	v_rcp_f32_e32 v169, v169
	v_exp_f32_e32 v170, v170
	v_mul_f32_e32 v169, v95, v169
	v_mul_f32_e32 v91, v169, v91
	v_add_f32_e32 v170, 1.0, v170
	v_rcp_f32_e32 v170, v170
	v_mul_f32_e32 v171, 0xbfb8aa3b, v85
	v_mul_f32_e32 v84, v84, v170
	v_mul_f32_e32 v92, v84, v80
	v_exp_f32_e32 v171, v171
	v_mul_f32_e32 v172, 0xbfb8aa3b, v86
	v_add_f32_e32 v171, 1.0, v171
	v_rcp_f32_e32 v171, v171
	v_exp_f32_e32 v172, v172
	v_mul_f32_e32 v171, v85, v171
	v_mul_f32_e32 v93, v171, v81
	v_lshl_add_u64 v[84:85], v[96:97], 0, v[112:113]
	v_add_f32_e32 v172, 1.0, v172
	v_rcp_f32_e32 v172, v172
	v_mul_f32_e32 v173, 0xbfb8aa3b, v87
	v_mul_f32_e32 v172, v86, v172
	v_mul_f32_e32 v86, v172, v82
	v_exp_f32_e32 v173, v173
	v_cvt_pk_bf16_f32 v80, v88, v89
	v_add_f32_e32 v173, 1.0, v173
	v_rcp_f32_e32 v173, v173
	v_cvt_pk_bf16_f32 v81, v90, v91
	v_mul_f32_e32 v173, v87, v173
	v_mul_f32_e32 v83, v173, v83
	v_cvt_pk_bf16_f32 v82, v92, v93
	v_cvt_pk_bf16_f32 v83, v86, v83
	v_mul_f32_e32 v174, 0xbfb8aa3b, v76
	global_store_dwordx4 v[84:85], v[80:83], off
; __device__ __forceinline__ unsigned cvt_pk_bf16(float lo, float hi) { unsigned r; asm volatile("v_cvt_pk_bf16_f32 %0, %1, %2" : "=v"(r) : "v"(lo), "v"(hi)); return r; }
;     DI void operator()(const pg8::f32x4 (&acc)[2][2][4][2], const pg8::Unit& u, int wr, int wc, int fr, int fq) const {
;     ...
;             for (int m = 0; m < 4; ++m) { bf16* rowp = O + (size_t)(row0 + ai * 128 + m * 16) * FF + col0;
;                 float hv[8];
; #pragma unroll
;                 for (int n = 0; n < 2; ++n)
; #pragma unroll
;                     for (int j = 0; j < 4; ++j) { const float g = acc[ai][0][m][n][j], up = acc[ai][1][m][n][j]; hv[4 * n + j] = g * __builtin_amdgcn_rcpf(1.f + __expf(-g)) * up; }
;                 v4u w; w.x = pg8::cvt_pk_bf16(hv[0], hv[1]); w.y = pg8::cvt_pk_bf16(hv[2], hv[3]); w.z = pg8::cvt_pk_bf16(hv[4], hv[5]); w.w = pg8::cvt_pk_bf16(hv[6], hv[7]);
;                 *(v4u*)rowp = w; }
	v_exp_f32_e32 v174, v174
	s_nop 0
	v_or_b32_e32 v80, 48, v144
	v_mad_i64_i32 v[80:81], s[14:15], v80, s7, v[138:139]
	v_add_f32_e32 v174, 1.0, v174
	v_rcp_f32_e32 v174, v174
	v_mul_f32_e32 v175, 0xbfb8aa3b, v77
	v_mul_f32_e32 v76, v76, v174
	v_mul_f32_e32 v72, v76, v72
	v_exp_f32_e32 v175, v175
	v_mul_f32_e32 v176, 0xbfb8aa3b, v78
	v_add_f32_e32 v175, 1.0, v175
	v_rcp_f32_e32 v175, v175
	v_exp_f32_e32 v176, v176
	v_mul_f32_e32 v175, v77, v175
	v_mul_f32_e32 v73, v175, v73
	v_add_f32_e32 v176, 1.0, v176
	v_rcp_f32_e32 v176, v176
	v_mul_f32_e32 v177, 0xbfb8aa3b, v79
	v_mul_f32_e32 v176, v78, v176
	v_mul_f32_e32 v74, v176, v74
	v_exp_f32_e32 v177, v177
	v_mul_f32_e32 v178, 0xbfb8aa3b, v68
	v_add_f32_e32 v177, 1.0, v177
	v_rcp_f32_e32 v177, v177
	v_exp_f32_e32 v178, v178
	v_mul_f32_e32 v177, v79, v177
	v_mul_f32_e32 v75, v177, v75
	v_add_f32_e32 v178, 1.0, v178
	v_rcp_f32_e32 v178, v178
	v_mul_f32_e32 v179, 0xbfb8aa3b, v69
	v_mul_f32_e32 v68, v68, v178
	v_mul_f32_e32 v76, v68, v64
	v_exp_f32_e32 v179, v179
	v_mul_f32_e32 v180, 0xbfb8aa3b, v70
	v_add_f32_e32 v179, 1.0, v179
	v_rcp_f32_e32 v179, v179
	v_exp_f32_e32 v180, v180
	v_mul_f32_e32 v179, v69, v179
	v_mul_f32_e32 v77, v179, v65
	v_lshl_add_u64 v[68:69], v[80:81], 0, v[112:113]
	v_add_f32_e32 v180, 1.0, v180
	v_rcp_f32_e32 v180, v180
	v_mul_f32_e32 v181, 0xbfb8aa3b, v71
	v_mul_f32_e32 v180, v70, v180
	v_mul_f32_e32 v70, v180, v66
	v_exp_f32_e32 v181, v181
	v_cvt_pk_bf16_f32 v64, v72, v73
	v_add_f32_e32 v181, 1.0, v181
	v_rcp_f32_e32 v181, v181
	v_cvt_pk_bf16_f32 v65, v74, v75
	v_mul_f32_e32 v181, v71, v181
	v_mul_f32_e32 v67, v181, v67
	v_cvt_pk_bf16_f32 v66, v76, v77
	v_cvt_pk_bf16_f32 v67, v70, v67
	v_mul_f32_e32 v150, 0xbfb8aa3b, v60
	global_store_dwordx4 v[68:69], v[64:67], off
	v_exp_f32_e32 v150, v150
	s_nop 0
	v_add_u32_e32 v64, 0x80, v144
	v_mad_i64_i32 v[64:65], s[14:15], v64, s7, v[138:139]
	v_add_f32_e32 v150, 1.0, v150
	v_rcp_f32_e32 v150, v150
	v_mul_f32_e32 v151, 0xbfb8aa3b, v61
	v_mul_f32_e32 v60, v60, v150
	v_mul_f32_e32 v56, v60, v56
	v_exp_f32_e32 v151, v151
	v_mul_f32_e32 v152, 0xbfb8aa3b, v62
	v_add_f32_e32 v151, 1.0, v151
	v_rcp_f32_e32 v151, v151
	v_exp_f32_e32 v152, v152
	v_mul_f32_e32 v151, v61, v151
	v_mul_f32_e32 v57, v151, v57
	v_add_f32_e32 v152, 1.0, v152
	v_rcp_f32_e32 v152, v152
	v_mul_f32_e32 v153, 0xbfb8aa3b, v63
	v_mul_f32_e32 v152, v62, v152
	v_mul_f32_e32 v58, v152, v58
	v_exp_f32_e32 v153, v153
	v_mul_f32_e32 v154, 0xbfb8aa3b, v52
	v_add_f32_e32 v153, 1.0, v153
	v_rcp_f32_e32 v153, v153
	v_exp_f32_e32 v154, v154
	v_mul_f32_e32 v153, v63, v153
	v_mul_f32_e32 v59, v153, v59
	v_add_f32_e32 v154, 1.0, v154
	v_rcp_f32_e32 v154, v154
	v_mul_f32_e32 v155, 0xbfb8aa3b, v53
	v_mul_f32_e32 v52, v52, v154
	v_mul_f32_e32 v60, v52, v48
	v_exp_f32_e32 v155, v155
	v_mul_f32_e32 v156, 0xbfb8aa3b, v54
	v_add_f32_e32 v155, 1.0, v155
	v_rcp_f32_e32 v155, v155
	v_exp_f32_e32 v156, v156
	v_mul_f32_e32 v155, v53, v155
	v_mul_f32_e32 v61, v155, v49
	v_lshl_add_u64 v[52:53], v[64:65], 0, v[112:113]
	v_add_f32_e32 v156, 1.0, v156
	v_rcp_f32_e32 v156, v156
	v_mul_f32_e32 v157, 0xbfb8aa3b, v55
	v_mul_f32_e32 v156, v54, v156
	v_mul_f32_e32 v54, v156, v50
	v_exp_f32_e32 v157, v157
	v_cvt_pk_bf16_f32 v48, v56, v57
	v_add_f32_e32 v157, 1.0, v157
	v_rcp_f32_e32 v157, v157
	v_cvt_pk_bf16_f32 v49, v58, v59
	v_mul_f32_e32 v157, v55, v157
	v_mul_f32_e32 v51, v157, v51
	v_cvt_pk_bf16_f32 v50, v60, v61
	v_cvt_pk_bf16_f32 v51, v54, v51
	v_mul_f32_e32 v158, 0xbfb8aa3b, v44
	global_store_dwordx4 v[52:53], v[48:51], off
	v_exp_f32_e32 v158, v158
	s_nop 0
	v_add_u32_e32 v48, 0x90, v144
	v_mad_i64_i32 v[48:49], s[14:15], v48, s7, v[138:139]
	v_add_f32_e32 v158, 1.0, v158
	v_rcp_f32_e32 v158, v158
	v_mul_f32_e32 v159, 0xbfb8aa3b, v45
	v_mul_f32_e32 v44, v44, v158
	v_mul_f32_e32 v40, v44, v40
	v_exp_f32_e32 v159, v159
	v_mul_f32_e32 v160, 0xbfb8aa3b, v46
	v_add_f32_e32 v159, 1.0, v159
	v_rcp_f32_e32 v159, v159
	v_exp_f32_e32 v160, v160
	v_mul_f32_e32 v159, v45, v159
	v_mul_f32_e32 v41, v159, v41
	v_add_f32_e32 v160, 1.0, v160
	v_rcp_f32_e32 v160, v160
	v_mul_f32_e32 v161, 0xbfb8aa3b, v47
	v_mul_f32_e32 v160, v46, v160
	v_mul_f32_e32 v42, v160, v42
	v_exp_f32_e32 v161, v161
	v_mul_f32_e32 v162, 0xbfb8aa3b, v36
	v_add_f32_e32 v161, 1.0, v161
	v_rcp_f32_e32 v161, v161
	v_exp_f32_e32 v162, v162
	v_mul_f32_e32 v161, v47, v161
	v_mul_f32_e32 v43, v161, v43
	v_add_f32_e32 v162, 1.0, v162
	v_rcp_f32_e32 v162, v162
	v_mul_f32_e32 v163, 0xbfb8aa3b, v37
; __device__ __forceinline__ unsigned cvt_pk_bf16(float lo, float hi) { unsigned r; asm volatile("v_cvt_pk_bf16_f32 %0, %1, %2" : "=v"(r) : "v"(lo), "v"(hi)); return r; }
;     DI void operator()(const pg8::f32x4 (&acc)[2][2][4][2], const pg8::Unit& u, int wr, int wc, int fr, int fq) const {
;     ...
;             for (int m = 0; m < 4; ++m) { bf16* rowp = O + (size_t)(row0 + ai * 128 + m * 16) * FF + col0;
;                 float hv[8];
; #pragma unroll
;                 for (int n = 0; n < 2; ++n)
; #pragma unroll
;                     for (int j = 0; j < 4; ++j) { const float g = acc[ai][0][m][n][j], up = acc[ai][1][m][n][j]; hv[4 * n + j] = g * __builtin_amdgcn_rcpf(1.f + __expf(-g)) * up; }
;                 v4u w; w.x = pg8::cvt_pk_bf16(hv[0], hv[1]); w.y = pg8::cvt_pk_bf16(hv[2], hv[3]); w.z = pg8::cvt_pk_bf16(hv[4], hv[5]); w.w = pg8::cvt_pk_bf16(hv[6], hv[7]);
;                 *(v4u*)rowp = w; }
	v_mul_f32_e32 v36, v36, v162
	v_mul_f32_e32 v44, v36, v32
	v_exp_f32_e32 v163, v163
	v_mul_f32_e32 v164, 0xbfb8aa3b, v38
	v_add_f32_e32 v163, 1.0, v163
	v_rcp_f32_e32 v163, v163
	v_exp_f32_e32 v164, v164
	v_mul_f32_e32 v163, v37, v163
	v_mul_f32_e32 v45, v163, v33
	v_lshl_add_u64 v[36:37], v[48:49], 0, v[112:113]
	v_add_f32_e32 v164, 1.0, v164
	v_rcp_f32_e32 v164, v164
	v_mul_f32_e32 v165, 0xbfb8aa3b, v39
	v_mul_f32_e32 v164, v38, v164
	v_mul_f32_e32 v38, v164, v34
	v_exp_f32_e32 v165, v165
	v_cvt_pk_bf16_f32 v32, v40, v41
	v_add_f32_e32 v165, 1.0, v165
	v_rcp_f32_e32 v165, v165
	v_cvt_pk_bf16_f32 v33, v42, v43
	v_mul_f32_e32 v165, v39, v165
	v_mul_f32_e32 v35, v165, v35
	v_cvt_pk_bf16_f32 v34, v44, v45
	v_cvt_pk_bf16_f32 v35, v38, v35
	v_mul_f32_e32 v166, 0xbfb8aa3b, v28
	global_store_dwordx4 v[36:37], v[32:35], off
	v_exp_f32_e32 v166, v166
	s_nop 0
	v_add_u32_e32 v32, 0xa0, v144
	v_mad_i64_i32 v[32:33], s[14:15], v32, s7, v[138:139]
	v_add_f32_e32 v166, 1.0, v166
	v_rcp_f32_e32 v166, v166
	v_mul_f32_e32 v167, 0xbfb8aa3b, v29
	v_mul_f32_e32 v28, v28, v166
	v_mul_f32_e32 v24, v28, v24
	v_exp_f32_e32 v167, v167
	v_mul_f32_e32 v168, 0xbfb8aa3b, v30
	v_add_f32_e32 v167, 1.0, v167
	v_rcp_f32_e32 v167, v167
	v_exp_f32_e32 v168, v168
	v_mul_f32_e32 v167, v29, v167
	v_mul_f32_e32 v25, v167, v25
	v_add_f32_e32 v168, 1.0, v168
	v_rcp_f32_e32 v168, v168
	v_mul_f32_e32 v169, 0xbfb8aa3b, v31
	v_mul_f32_e32 v168, v30, v168
	v_mul_f32_e32 v26, v168, v26
	v_exp_f32_e32 v169, v169
	v_mul_f32_e32 v170, 0xbfb8aa3b, v20
	v_add_f32_e32 v169, 1.0, v169
	v_rcp_f32_e32 v169, v169
	v_exp_f32_e32 v170, v170
	v_mul_f32_e32 v169, v31, v169
	v_mul_f32_e32 v27, v169, v27
	v_add_f32_e32 v170, 1.0, v170
	v_rcp_f32_e32 v170, v170
	v_mul_f32_e32 v171, 0xbfb8aa3b, v21
	v_mul_f32_e32 v20, v20, v170
	v_mul_f32_e32 v28, v20, v16
	v_exp_f32_e32 v171, v171
	v_mul_f32_e32 v172, 0xbfb8aa3b, v22
	v_add_f32_e32 v171, 1.0, v171
	v_rcp_f32_e32 v171, v171
	v_exp_f32_e32 v172, v172
	v_mul_f32_e32 v171, v21, v171
	v_mul_f32_e32 v29, v171, v17
	v_lshl_add_u64 v[20:21], v[32:33], 0, v[112:113]
	v_add_f32_e32 v172, 1.0, v172
	v_rcp_f32_e32 v172, v172
	v_mul_f32_e32 v173, 0xbfb8aa3b, v23
	v_mul_f32_e32 v172, v22, v172
	v_mul_f32_e32 v22, v172, v18
	v_exp_f32_e32 v173, v173
	v_cvt_pk_bf16_f32 v16, v24, v25
	v_add_f32_e32 v173, 1.0, v173
	v_rcp_f32_e32 v173, v173
	v_cvt_pk_bf16_f32 v17, v26, v27
	v_mul_f32_e32 v173, v23, v173
	v_mul_f32_e32 v19, v173, v19
	v_cvt_pk_bf16_f32 v18, v28, v29
	v_cvt_pk_bf16_f32 v19, v22, v19
	v_mul_f32_e32 v174, 0xbfb8aa3b, v12
	global_store_dwordx4 v[20:21], v[16:19], off
	v_exp_f32_e32 v174, v174
	s_nop 0
	v_add_u32_e32 v16, 0xb0, v144
	v_mad_i64_i32 v[16:17], s[14:15], v16, s7, v[138:139]
	v_add_f32_e32 v174, 1.0, v174
	v_rcp_f32_e32 v174, v174
	s_mov_b64 s[14:15], -1
	v_mul_f32_e32 v12, v12, v174
	v_mul_f32_e32 v8, v12, v8
	v_mul_f32_e32 v175, 0xbfb8aa3b, v13
	v_exp_f32_e32 v175, v175
	v_mul_f32_e32 v176, 0xbfb8aa3b, v14
	v_add_f32_e32 v175, 1.0, v175
	v_rcp_f32_e32 v175, v175
	v_exp_f32_e32 v176, v176
	v_mul_f32_e32 v175, v13, v175
	v_mul_f32_e32 v9, v175, v9
	v_add_f32_e32 v176, 1.0, v176
	v_rcp_f32_e32 v176, v176
	v_mul_f32_e32 v177, 0xbfb8aa3b, v15
	v_mul_f32_e32 v176, v14, v176
	v_mul_f32_e32 v10, v176, v10
	v_exp_f32_e32 v177, v177
	v_mul_f32_e32 v178, 0xbfb8aa3b, v4
	v_add_f32_e32 v177, 1.0, v177
	v_rcp_f32_e32 v177, v177
	v_exp_f32_e32 v178, v178
	v_mul_f32_e32 v177, v15, v177
	v_mul_f32_e32 v11, v177, v11
	v_add_f32_e32 v178, 1.0, v178
	v_rcp_f32_e32 v178, v178
	v_mul_f32_e32 v179, 0xbfb8aa3b, v5
	v_mul_f32_e32 v4, v4, v178
	v_mul_f32_e32 v12, v4, v0
	v_exp_f32_e32 v179, v179
	v_mul_f32_e32 v180, 0xbfb8aa3b, v6
	v_add_f32_e32 v179, 1.0, v179
	v_rcp_f32_e32 v179, v179
	v_exp_f32_e32 v180, v180
	v_mul_f32_e32 v179, v5, v179
	v_mul_f32_e32 v13, v179, v1
	v_lshl_add_u64 v[4:5], v[16:17], 0, v[112:113]
	v_add_f32_e32 v180, 1.0, v180
	v_rcp_f32_e32 v180, v180
	v_mul_f32_e32 v181, 0xbfb8aa3b, v7
	v_mul_f32_e32 v180, v6, v180
	v_mul_f32_e32 v6, v180, v2
	v_exp_f32_e32 v181, v181
	v_cvt_pk_bf16_f32 v0, v8, v9
	v_add_f32_e32 v181, 1.0, v181
	v_rcp_f32_e32 v181, v181
	v_cvt_pk_bf16_f32 v1, v10, v11
	v_mul_f32_e32 v181, v7, v181
	v_mul_f32_e32 v3, v181, v3
	v_cvt_pk_bf16_f32 v2, v12, v13
	v_cvt_pk_bf16_f32 v3, v6, v3
	s_nop 0
	global_store_dwordx4 v[4:5], v[0:3], off
	s_cbranch_vccnz .LBB0_1172
	s_andn2_b64 vcc, exec, s[0:1]
	s_cbranch_vccnz .LBB0_1171
	s_barrier
	s_branch .LBB0_1171
